# split grid barrier between scan_states and phase 6: arrive after the scan, wait after the attention items (which do not read phase-5 data); plus 4-byte placement pads before proj/ffnup1 glds loops
# speedup vs baseline: 1.0067x; 1.0067x over previous
.LBB0_872:
	s_or_b64 exec, exec, s[12:13]
	v_cvt_f32_u32_e32 v4, v2
	s_waitcnt vmcnt(0)
	v_readfirstlane_b32 s10, v3
	v_sub_u32_e32 v3, 0, v2
	v_rcp_iflag_f32_e32 v4, v4
	v_add_u32_e32 v5, s10, v1
	v_mul_f32_e32 v4, 0x4f7ffffe, v4
	v_cvt_u32_f32_e32 v4, v4
	v_mul_lo_u32 v1, v3, v4
	v_mul_hi_u32 v1, v4, v1
	v_add_u32_e32 v1, v4, v1
	v_mul_hi_u32 v1, v5, v1
	v_mul_lo_u32 v3, v1, v2
	v_sub_u32_e32 v3, v5, v3
	v_add_u32_e32 v4, 1, v1
	v_cmp_ge_u32_e32 vcc, v3, v2
	s_nop 1
	v_cndmask_b32_e32 v1, v1, v4, vcc
	v_sub_u32_e32 v4, v3, v2
	v_cndmask_b32_e32 v3, v3, v4, vcc
	v_add_u32_e32 v4, 1, v1
	v_cmp_ge_u32_e32 vcc, v3, v2
	v_add_u32_e32 v3, 1, v5
	s_nop 0
	v_cndmask_b32_e32 v1, v1, v4, vcc
	v_mul_lo_u32 v4, v2, v1
	v_add_u32_e32 v2, v4, v2
	v_cmp_ne_u32_e32 vcc, v3, v2
	s_and_saveexec_b64 s[10:11], vcc
	s_xor_b64 s[10:11], exec, s[10:11]
	s_cbranch_execz .LBB0_886
	s_waitcnt lgkmcnt(0)
	buffer_inv sc1
	v_mov_b32_e32 v0, 0x24008
	ds_write_b32 v0, v1
	s_waitcnt vmcnt(0)
	s_waitcnt vmcnt(0)

.LBB0_889:
	s_or_b64 exec, exec, s[12:13]
	buffer_inv sc1
	v_cvt_f32_u32_e32 v3, v0
	s_waitcnt vmcnt(0)
	v_readfirstlane_b32 s10, v2
	s_add_u32 s12, s34, 0xed10500
	s_addc_u32 s13, s35, 0
	v_rcp_iflag_f32_e32 v3, v3
	v_add_u32_e32 v1, s10, v1
	v_add_u32_e32 v4, 1, v1
	s_mov_b64 s[16:17], -1
	v_mul_f32_e32 v2, 0x4f7ffffe, v3
	v_cvt_u32_f32_e32 v2, v2
	v_sub_u32_e32 v3, 0, v0
	v_mul_lo_u32 v3, v3, v2
	v_mul_hi_u32 v3, v2, v3
	v_add_u32_e32 v2, v2, v3
	v_mul_hi_u32 v2, v1, v2
	v_mul_lo_u32 v3, v2, v0
	v_sub_u32_e32 v1, v1, v3
	v_add_u32_e32 v5, 1, v2
	v_cmp_ge_u32_e32 vcc, v1, v0
	v_sub_u32_e32 v3, v1, v0
	s_nop 0
	v_cndmask_b32_e32 v2, v2, v5, vcc
	v_cndmask_b32_e32 v1, v1, v3, vcc
	v_add_u32_e32 v3, 1, v2
	v_cmp_ge_u32_e32 vcc, v1, v0
	s_nop 1
	v_cndmask_b32_e32 v2, v2, v3, vcc
	v_mul_lo_u32 v1, v0, v2
	v_add_u32_e32 v0, v1, v0
	v_mov_b32_e32 v3, 0x24008
	ds_write_b32 v3, v2
	v_cmp_ne_u32_e32 vcc, v4, v0
	v_mov_b64_e32 v[0:1], s[12:13]
	s_and_saveexec_b64 s[10:11], vcc
	s_cbranch_execz .LBB0_901
	s_mov_b64 s[16:17], 0

.LBB0_931:
	s_waitcnt lgkmcnt(0)
	s_cmp_gt_i32 s88, 5
	s_cbranch_scc1 .Lsb_skip
	s_and_saveexec_b64 s[16:17], s[92:93]
	s_cbranch_execz .Lsb_done
	v_mov_b32_e32 v0, 0x24008
	ds_read_b32 v1, v0
	buffer_inv sc1
	s_add_u32 s18, s34, 0xed10500
	s_addc_u32 s19, s35, 0
	v_mov_b32_e32 v0, 0
	s_mov_b32 s20, 0
	s_waitcnt lgkmcnt(0)
.Lsb_poll:
	global_load_dword v2, v0, s[18:19] sc1
	s_add_u32 s20, s20, 1
	s_waitcnt vmcnt(0)
	v_cmp_eq_u32_e32 vcc, v2, v1
	s_cbranch_vccz .Lsb_done
	s_sleep 1
	s_cmp_lt_u32 s20, 0x400000
	s_cbranch_scc1 .Lsb_poll
.Lsb_done:
	s_or_b64 exec, exec, s[16:17]
	s_barrier
